# baseline (speedup 1.0000x reference)
; __device__ __forceinline__ int olane() { int l; asm volatile("v_mbcnt_lo_u32_b32 %0, -1, 0\n\tv_mbcnt_hi_u32_b32 %0, -1, %0" : "=v"(l)); return l; }
; __global__ void __launch_bounds__(NTHREADS, 2) fwd_kernel(Params a) {
;     ...
;         if (ph + 1 < a.p1) {
;             if (ph == a.p0) grid.sync();
;             else { const bool leader = (wv == 0) && (olane() == 0); xcd_barrier(xb, leader); }
.LBB0_2037:
	s_cmp_lg_u32 s20, s38
	v_readlane_b32 s20, v253, 25
	v_readlane_b32 s22, v253, 27
	v_readlane_b32 s26, v253, 29
	v_readlane_b32 s28, v253, 31
	v_readlane_b32 s21, v253, 26
	v_readlane_b32 s23, v253, 28
	v_readlane_b32 s27, v253, 30
	v_readlane_b32 s29, v253, 32
	v_readlane_b32 s0, v253, 21
	v_readlane_b32 s1, v253, 22
	s_andn2_b64 vcc, exec, s[0:1]
	s_mov_b64 s[8:9], 0
	s_cbranch_vccnz .LBB0_2040
	v_mbcnt_lo_u32_b32 v0, -1, 0
	v_mbcnt_hi_u32_b32 v0, -1, v0
	s_nop 0
	v_cmp_eq_u32_e32 vcc, 0, v0
	s_and_b64 s[8:9], vcc, exec
